# ResGate GEMM epilogue (w_out, ff2) de-serialized: 12 x-loads in flight with counted vmcnt instead of a 32-step load/wait/store ladder
# speedup vs baseline: 1.0167x; 1.0167x over previous
.LBB0_1844:
	s_add_u32 s23, s66, s48
	s_addc_u32 s25, s67, s49
	s_lshl_b32 s36, s36, 8
	s_ashr_i32 s37, s36, 31
	s_lshl_b64 s[46:47], s[36:37], 2
	v_mov_b32_e32 v171, s37
	v_or_b32_e32 v170, s36, v148
	s_add_u32 s23, s23, s46
	s_addc_u32 s25, s25, s47
	s_add_u32 s46, s23, s57
	s_addc_u32 s47, s25, 0
	global_load_dwordx4 v[142:145], v173, s[46:47]
	global_load_dwordx4 v[138:141], v173, s[46:47] offset:64
	global_load_dwordx4 v[134:137], v173, s[46:47] offset:512
	global_load_dwordx4 v[130:133], v173, s[46:47] offset:576
	s_add_u32 s36, s16, s44
	s_addc_u32 s37, s17, s45
	s_andn2_b64 vcc, exec, s[26:27]
	s_mov_b64 s[26:27], -1
	s_sub_u32 s44, s36, s42
	s_subb_u32 s45, s37, s43
	v_lshl_add_u64 v[174:175], v[170:171], 0, v[150:151]
	v_lshlrev_b64 v[174:175], 2, v[174:175]
	v_lshl_add_u64 v[174:175], s[42:43], 0, v[174:175]
	global_load_dwordx4 v[184:187], v[174:175], off
	global_load_dwordx4 v[190:193], v[174:175], off offset:64
	global_load_dwordx4 v[194:197], v[174:175], off offset:512
	global_load_dwordx4 v[198:201], v[174:175], off offset:576
	v_lshl_add_u64 v[176:177], v[170:171], 0, v[152:153]
	v_lshlrev_b64 v[176:177], 2, v[176:177]
	v_lshl_add_u64 v[176:177], s[42:43], 0, v[176:177]
	global_load_dwordx4 v[202:205], v[176:177], off
	global_load_dwordx4 v[206:209], v[176:177], off offset:64
	global_load_dwordx4 v[210:213], v[176:177], off offset:512
	global_load_dwordx4 v[214:217], v[176:177], off offset:576
	v_lshl_add_u64 v[180:181], v[170:171], 0, v[154:155]
	v_lshlrev_b64 v[180:181], 2, v[180:181]
	v_lshl_add_u64 v[180:181], s[42:43], 0, v[180:181]
	global_load_dwordx4 v[218:221], v[180:181], off
	global_load_dwordx4 v[222:225], v[180:181], off offset:64
	global_load_dwordx4 v[226:229], v[180:181], off offset:512
	global_load_dwordx4 v[230:233], v[180:181], off offset:576
	s_waitcnt vmcnt(8)
	v_pk_fma_f32 v[186:187], v[128:129], v[144:145], v[186:187]
	v_pk_fma_f32 v[184:185], v[126:127], v[142:143], v[184:185]
	v_pk_fma_f32 v[192:193], v[124:125], v[140:141], v[192:193]
	v_pk_fma_f32 v[190:191], v[122:123], v[138:139], v[190:191]
	v_pk_fma_f32 v[196:197], v[120:121], v[136:137], v[196:197]
	v_pk_fma_f32 v[194:195], v[118:119], v[134:135], v[194:195]
	v_pk_fma_f32 v[200:201], v[108:109], v[132:133], v[200:201]
	v_pk_fma_f32 v[198:199], v[106:107], v[130:131], v[198:199]
	v_lshl_add_u64 v[182:183], v[174:175], 0, s[44:45]
	global_store_dwordx4 v[182:183], v[184:187], off
	global_store_dwordx4 v[182:183], v[190:193], off offset:64
	global_store_dwordx4 v[182:183], v[194:197], off offset:512
	global_store_dwordx4 v[182:183], v[198:201], off offset:576
	v_lshl_add_u64 v[174:175], v[170:171], 0, v[156:157]
	v_lshlrev_b64 v[174:175], 2, v[174:175]
	v_lshl_add_u64 v[174:175], s[42:43], 0, v[174:175]
	global_load_dwordx4 v[184:187], v[174:175], off
	global_load_dwordx4 v[190:193], v[174:175], off offset:64
	global_load_dwordx4 v[194:197], v[174:175], off offset:512
	global_load_dwordx4 v[198:201], v[174:175], off offset:576
	s_waitcnt vmcnt(12)
	v_pk_fma_f32 v[204:205], v[116:117], v[144:145], v[204:205]
	v_pk_fma_f32 v[202:203], v[114:115], v[142:143], v[202:203]
	v_pk_fma_f32 v[208:209], v[112:113], v[140:141], v[208:209]
	v_pk_fma_f32 v[206:207], v[110:111], v[138:139], v[206:207]
	v_pk_fma_f32 v[212:213], v[104:105], v[136:137], v[212:213]
	v_pk_fma_f32 v[210:211], v[102:103], v[134:135], v[210:211]
	v_pk_fma_f32 v[216:217], v[90:91], v[132:133], v[216:217]
	v_pk_fma_f32 v[214:215], v[88:89], v[130:131], v[214:215]
	v_lshl_add_u64 v[182:183], v[176:177], 0, s[44:45]
	global_store_dwordx4 v[182:183], v[202:205], off
	global_store_dwordx4 v[182:183], v[206:209], off offset:64
	global_store_dwordx4 v[182:183], v[210:213], off offset:512
	global_store_dwordx4 v[182:183], v[214:217], off offset:576
	v_lshl_add_u64 v[176:177], v[170:171], 0, v[158:159]
	v_lshlrev_b64 v[176:177], 2, v[176:177]
	v_lshl_add_u64 v[176:177], s[42:43], 0, v[176:177]
	global_load_dwordx4 v[202:205], v[176:177], off
	global_load_dwordx4 v[206:209], v[176:177], off offset:64
	global_load_dwordx4 v[210:213], v[176:177], off offset:512
	global_load_dwordx4 v[214:217], v[176:177], off offset:576
	s_waitcnt vmcnt(16)
	v_pk_fma_f32 v[220:221], v[100:101], v[144:145], v[220:221]
	v_pk_fma_f32 v[218:219], v[98:99], v[142:143], v[218:219]
	v_pk_fma_f32 v[224:225], v[94:95], v[140:141], v[224:225]
	v_pk_fma_f32 v[222:223], v[92:93], v[138:139], v[222:223]
	v_pk_fma_f32 v[228:229], v[86:87], v[136:137], v[228:229]
	v_pk_fma_f32 v[226:227], v[84:85], v[134:135], v[226:227]
	v_pk_fma_f32 v[232:233], v[74:75], v[132:133], v[232:233]
	v_pk_fma_f32 v[230:231], v[72:73], v[130:131], v[230:231]
	v_lshl_add_u64 v[182:183], v[180:181], 0, s[44:45]
	global_store_dwordx4 v[182:183], v[218:221], off
	global_store_dwordx4 v[182:183], v[222:225], off offset:64
	global_store_dwordx4 v[182:183], v[226:229], off offset:512
	global_store_dwordx4 v[182:183], v[230:233], off offset:576
	v_lshl_add_u64 v[180:181], v[170:171], 0, v[160:161]
	v_lshlrev_b64 v[180:181], 2, v[180:181]
	v_lshl_add_u64 v[180:181], s[42:43], 0, v[180:181]
	global_load_dwordx4 v[218:221], v[180:181], off
	global_load_dwordx4 v[222:225], v[180:181], off offset:64
	global_load_dwordx4 v[226:229], v[180:181], off offset:512
	global_load_dwordx4 v[230:233], v[180:181], off offset:576
	s_waitcnt vmcnt(16)
	v_pk_fma_f32 v[186:187], v[82:83], v[144:145], v[186:187]
	v_pk_fma_f32 v[184:185], v[80:81], v[142:143], v[184:185]
	v_pk_fma_f32 v[192:193], v[78:79], v[140:141], v[192:193]
	v_pk_fma_f32 v[190:191], v[76:77], v[138:139], v[190:191]
	v_pk_fma_f32 v[196:197], v[70:71], v[136:137], v[196:197]
	v_pk_fma_f32 v[194:195], v[68:69], v[134:135], v[194:195]
	v_pk_fma_f32 v[200:201], v[66:67], v[132:133], v[200:201]
	v_pk_fma_f32 v[198:199], v[64:65], v[130:131], v[198:199]
	v_lshl_add_u64 v[182:183], v[174:175], 0, s[44:45]
	global_store_dwordx4 v[182:183], v[184:187], off
	global_store_dwordx4 v[182:183], v[190:193], off offset:64
	global_store_dwordx4 v[182:183], v[194:197], off offset:512
	global_store_dwordx4 v[182:183], v[198:201], off offset:576
	v_lshl_add_u64 v[174:175], v[170:171], 0, v[162:163]
	v_lshlrev_b64 v[174:175], 2, v[174:175]
	v_lshl_add_u64 v[174:175], s[42:43], 0, v[174:175]
	global_load_dwordx4 v[184:187], v[174:175], off
	global_load_dwordx4 v[190:193], v[174:175], off offset:64
	global_load_dwordx4 v[194:197], v[174:175], off offset:512
	global_load_dwordx4 v[198:201], v[174:175], off offset:576
	s_waitcnt vmcnt(16)
	v_pk_fma_f32 v[204:205], v[62:63], v[144:145], v[204:205]
	v_pk_fma_f32 v[202:203], v[60:61], v[142:143], v[202:203]
	v_pk_fma_f32 v[208:209], v[58:59], v[140:141], v[208:209]
	v_pk_fma_f32 v[206:207], v[56:57], v[138:139], v[206:207]
	v_pk_fma_f32 v[212:213], v[54:55], v[136:137], v[212:213]
	v_pk_fma_f32 v[210:211], v[52:53], v[134:135], v[210:211]
	v_pk_fma_f32 v[216:217], v[42:43], v[132:133], v[216:217]
	v_pk_fma_f32 v[214:215], v[40:41], v[130:131], v[214:215]
	v_lshl_add_u64 v[182:183], v[176:177], 0, s[44:45]
	global_store_dwordx4 v[182:183], v[202:205], off
	global_store_dwordx4 v[182:183], v[206:209], off offset:64
	global_store_dwordx4 v[182:183], v[210:213], off offset:512
	global_store_dwordx4 v[182:183], v[214:217], off offset:576
	v_lshl_add_u64 v[176:177], v[170:171], 0, v[164:165]
	v_lshlrev_b64 v[176:177], 2, v[176:177]
	v_lshl_add_u64 v[176:177], s[42:43], 0, v[176:177]
	global_load_dwordx4 v[202:205], v[176:177], off
	global_load_dwordx4 v[206:209], v[176:177], off offset:64
	global_load_dwordx4 v[210:213], v[176:177], off offset:512
	global_load_dwordx4 v[214:217], v[176:177], off offset:576
	s_waitcnt vmcnt(16)
	v_pk_fma_f32 v[220:221], v[50:51], v[144:145], v[220:221]
	v_pk_fma_f32 v[218:219], v[48:49], v[142:143], v[218:219]
	v_pk_fma_f32 v[224:225], v[46:47], v[140:141], v[224:225]
	v_pk_fma_f32 v[222:223], v[44:45], v[138:139], v[222:223]
	v_pk_fma_f32 v[228:229], v[38:39], v[136:137], v[228:229]
	v_pk_fma_f32 v[226:227], v[36:37], v[134:135], v[226:227]
	v_pk_fma_f32 v[232:233], v[26:27], v[132:133], v[232:233]
	v_pk_fma_f32 v[230:231], v[24:25], v[130:131], v[230:231]
	v_lshl_add_u64 v[182:183], v[180:181], 0, s[44:45]
	global_store_dwordx4 v[182:183], v[218:221], off
	global_store_dwordx4 v[182:183], v[222:225], off offset:64
	global_store_dwordx4 v[182:183], v[226:229], off offset:512
	global_store_dwordx4 v[182:183], v[230:233], off offset:576
	s_waitcnt vmcnt(12)
	v_pk_fma_f32 v[186:187], v[34:35], v[144:145], v[186:187]
	v_pk_fma_f32 v[184:185], v[32:33], v[142:143], v[184:185]
	v_pk_fma_f32 v[192:193], v[30:31], v[140:141], v[192:193]
	v_pk_fma_f32 v[190:191], v[28:29], v[138:139], v[190:191]
	v_pk_fma_f32 v[196:197], v[22:23], v[136:137], v[196:197]
	v_pk_fma_f32 v[194:195], v[20:21], v[134:135], v[194:195]
	v_pk_fma_f32 v[200:201], v[10:11], v[132:133], v[200:201]
	v_pk_fma_f32 v[198:199], v[8:9], v[130:131], v[198:199]
	v_lshl_add_u64 v[182:183], v[174:175], 0, s[44:45]
	global_store_dwordx4 v[182:183], v[184:187], off
	global_store_dwordx4 v[182:183], v[190:193], off offset:64
	global_store_dwordx4 v[182:183], v[194:197], off offset:512
	global_store_dwordx4 v[182:183], v[198:201], off offset:576
	s_waitcnt vmcnt(8)
	v_pk_fma_f32 v[204:205], v[18:19], v[144:145], v[204:205]
	v_pk_fma_f32 v[202:203], v[16:17], v[142:143], v[202:203]
	v_pk_fma_f32 v[208:209], v[14:15], v[140:141], v[208:209]
	v_pk_fma_f32 v[206:207], v[12:13], v[138:139], v[206:207]
	v_pk_fma_f32 v[212:213], v[6:7], v[136:137], v[212:213]
	v_pk_fma_f32 v[210:211], v[4:5], v[134:135], v[210:211]
	v_pk_fma_f32 v[216:217], v[2:3], v[132:133], v[216:217]
	v_pk_fma_f32 v[214:215], v[0:1], v[130:131], v[214:215]
	v_lshl_add_u64 v[182:183], v[176:177], 0, s[44:45]
	global_store_dwordx4 v[182:183], v[202:205], off
	global_store_dwordx4 v[182:183], v[206:209], off offset:64
	global_store_dwordx4 v[182:183], v[210:213], off offset:512
	global_store_dwordx4 v[182:183], v[214:217], off offset:576
	s_cbranch_vccnz .LBB0_1833
	s_andn2_b64 vcc, exec, s[18:19]
	s_cbranch_vccnz .LBB0_1832
	s_barrier
	s_branch .LBB0_1832

.LBB0_2028:
	s_add_u32 s21, s52, s46
	s_addc_u32 s23, s53, s47
	s_lshl_b32 s30, s30, 8
	s_ashr_i32 s31, s30, 31
	s_lshl_b64 s[44:45], s[30:31], 2
	v_mov_b32_e32 v173, s31
	v_or_b32_e32 v172, s30, v148
	s_add_u32 s21, s21, s44
	s_addc_u32 s23, s23, s45
	s_add_u32 s44, s21, s57
	s_addc_u32 s45, s23, 0
	global_load_dwordx4 v[142:145], v174, s[44:45]
	global_load_dwordx4 v[138:141], v174, s[44:45] offset:64
	global_load_dwordx4 v[134:137], v174, s[44:45] offset:512
	global_load_dwordx4 v[130:133], v174, s[44:45] offset:576
	s_add_u32 s30, s14, s42
	s_addc_u32 s31, s15, s43
	s_andn2_b64 vcc, exec, s[24:25]
	s_mov_b64 s[24:25], -1
	s_sub_u32 s42, s30, s36
	s_subb_u32 s43, s31, s37
	v_lshl_add_u64 v[180:181], v[172:173], 0, v[150:151]
	v_lshlrev_b64 v[180:181], 2, v[180:181]
	v_lshl_add_u64 v[180:181], s[36:37], 0, v[180:181]
	global_load_dwordx4 v[184:187], v[180:181], off
	global_load_dwordx4 v[190:193], v[180:181], off offset:64
	global_load_dwordx4 v[194:197], v[180:181], off offset:512
	global_load_dwordx4 v[198:201], v[180:181], off offset:576
	v_lshl_add_u64 v[182:183], v[172:173], 0, v[152:153]
	v_lshlrev_b64 v[182:183], 2, v[182:183]
	v_lshl_add_u64 v[182:183], s[36:37], 0, v[182:183]
	global_load_dwordx4 v[202:205], v[182:183], off
	global_load_dwordx4 v[206:209], v[182:183], off offset:64
	global_load_dwordx4 v[210:213], v[182:183], off offset:512
	global_load_dwordx4 v[214:217], v[182:183], off offset:576
	v_lshl_add_u64 v[176:177], v[172:173], 0, v[154:155]
	v_lshlrev_b64 v[176:177], 2, v[176:177]
	v_lshl_add_u64 v[176:177], s[36:37], 0, v[176:177]
	global_load_dwordx4 v[218:221], v[176:177], off
	global_load_dwordx4 v[222:225], v[176:177], off offset:64
	global_load_dwordx4 v[226:229], v[176:177], off offset:512
	global_load_dwordx4 v[230:233], v[176:177], off offset:576
	s_waitcnt vmcnt(8)
	v_pk_fma_f32 v[186:187], v[128:129], v[144:145], v[186:187]
	v_pk_fma_f32 v[184:185], v[126:127], v[142:143], v[184:185]
	v_pk_fma_f32 v[192:193], v[124:125], v[140:141], v[192:193]
	v_pk_fma_f32 v[190:191], v[122:123], v[138:139], v[190:191]
	v_pk_fma_f32 v[196:197], v[120:121], v[136:137], v[196:197]
	v_pk_fma_f32 v[194:195], v[118:119], v[134:135], v[194:195]
	v_pk_fma_f32 v[200:201], v[108:109], v[132:133], v[200:201]
	v_pk_fma_f32 v[198:199], v[106:107], v[130:131], v[198:199]
	v_lshl_add_u64 v[234:235], v[180:181], 0, s[42:43]
	global_store_dwordx4 v[234:235], v[184:187], off
	global_store_dwordx4 v[234:235], v[190:193], off offset:64
	global_store_dwordx4 v[234:235], v[194:197], off offset:512
	global_store_dwordx4 v[234:235], v[198:201], off offset:576
	v_lshl_add_u64 v[180:181], v[172:173], 0, v[156:157]
	v_lshlrev_b64 v[180:181], 2, v[180:181]
	v_lshl_add_u64 v[180:181], s[36:37], 0, v[180:181]
	global_load_dwordx4 v[184:187], v[180:181], off
	global_load_dwordx4 v[190:193], v[180:181], off offset:64
	global_load_dwordx4 v[194:197], v[180:181], off offset:512
	global_load_dwordx4 v[198:201], v[180:181], off offset:576
	s_waitcnt vmcnt(12)
	v_pk_fma_f32 v[204:205], v[116:117], v[144:145], v[204:205]
	v_pk_fma_f32 v[202:203], v[114:115], v[142:143], v[202:203]
	v_pk_fma_f32 v[208:209], v[112:113], v[140:141], v[208:209]
	v_pk_fma_f32 v[206:207], v[110:111], v[138:139], v[206:207]
	v_pk_fma_f32 v[212:213], v[104:105], v[136:137], v[212:213]
	v_pk_fma_f32 v[210:211], v[102:103], v[134:135], v[210:211]
	v_pk_fma_f32 v[216:217], v[90:91], v[132:133], v[216:217]
	v_pk_fma_f32 v[214:215], v[88:89], v[130:131], v[214:215]
	v_lshl_add_u64 v[234:235], v[182:183], 0, s[42:43]
	global_store_dwordx4 v[234:235], v[202:205], off
	global_store_dwordx4 v[234:235], v[206:209], off offset:64
	global_store_dwordx4 v[234:235], v[210:213], off offset:512
	global_store_dwordx4 v[234:235], v[214:217], off offset:576
	v_lshl_add_u64 v[182:183], v[172:173], 0, v[158:159]
	v_lshlrev_b64 v[182:183], 2, v[182:183]
	v_lshl_add_u64 v[182:183], s[36:37], 0, v[182:183]
	global_load_dwordx4 v[202:205], v[182:183], off
	global_load_dwordx4 v[206:209], v[182:183], off offset:64
	global_load_dwordx4 v[210:213], v[182:183], off offset:512
	global_load_dwordx4 v[214:217], v[182:183], off offset:576
	s_waitcnt vmcnt(16)
	v_pk_fma_f32 v[220:221], v[100:101], v[144:145], v[220:221]
	v_pk_fma_f32 v[218:219], v[98:99], v[142:143], v[218:219]
	v_pk_fma_f32 v[224:225], v[94:95], v[140:141], v[224:225]
	v_pk_fma_f32 v[222:223], v[92:93], v[138:139], v[222:223]
	v_pk_fma_f32 v[228:229], v[86:87], v[136:137], v[228:229]
	v_pk_fma_f32 v[226:227], v[84:85], v[134:135], v[226:227]
	v_pk_fma_f32 v[232:233], v[74:75], v[132:133], v[232:233]
	v_pk_fma_f32 v[230:231], v[72:73], v[130:131], v[230:231]
	v_lshl_add_u64 v[234:235], v[176:177], 0, s[42:43]
	global_store_dwordx4 v[234:235], v[218:221], off
	global_store_dwordx4 v[234:235], v[222:225], off offset:64
	global_store_dwordx4 v[234:235], v[226:229], off offset:512
	global_store_dwordx4 v[234:235], v[230:233], off offset:576
	v_lshl_add_u64 v[176:177], v[172:173], 0, v[160:161]
	v_lshlrev_b64 v[176:177], 2, v[176:177]
	v_lshl_add_u64 v[176:177], s[36:37], 0, v[176:177]
	global_load_dwordx4 v[218:221], v[176:177], off
	global_load_dwordx4 v[222:225], v[176:177], off offset:64
	global_load_dwordx4 v[226:229], v[176:177], off offset:512
	global_load_dwordx4 v[230:233], v[176:177], off offset:576
	s_waitcnt vmcnt(16)
	v_pk_fma_f32 v[186:187], v[82:83], v[144:145], v[186:187]
	v_pk_fma_f32 v[184:185], v[80:81], v[142:143], v[184:185]
	v_pk_fma_f32 v[192:193], v[78:79], v[140:141], v[192:193]
	v_pk_fma_f32 v[190:191], v[76:77], v[138:139], v[190:191]
	v_pk_fma_f32 v[196:197], v[70:71], v[136:137], v[196:197]
	v_pk_fma_f32 v[194:195], v[68:69], v[134:135], v[194:195]
	v_pk_fma_f32 v[200:201], v[66:67], v[132:133], v[200:201]
	v_pk_fma_f32 v[198:199], v[64:65], v[130:131], v[198:199]
	v_lshl_add_u64 v[234:235], v[180:181], 0, s[42:43]
	global_store_dwordx4 v[234:235], v[184:187], off
	global_store_dwordx4 v[234:235], v[190:193], off offset:64
	global_store_dwordx4 v[234:235], v[194:197], off offset:512
	global_store_dwordx4 v[234:235], v[198:201], off offset:576
	v_lshl_add_u64 v[180:181], v[172:173], 0, v[164:165]
	v_lshlrev_b64 v[180:181], 2, v[180:181]
	v_lshl_add_u64 v[180:181], s[36:37], 0, v[180:181]
	global_load_dwordx4 v[184:187], v[180:181], off
	global_load_dwordx4 v[190:193], v[180:181], off offset:64
	global_load_dwordx4 v[194:197], v[180:181], off offset:512
	global_load_dwordx4 v[198:201], v[180:181], off offset:576
	s_waitcnt vmcnt(16)
	v_pk_fma_f32 v[204:205], v[62:63], v[144:145], v[204:205]
	v_pk_fma_f32 v[202:203], v[60:61], v[142:143], v[202:203]
	v_pk_fma_f32 v[208:209], v[58:59], v[140:141], v[208:209]
	v_pk_fma_f32 v[206:207], v[56:57], v[138:139], v[206:207]
	v_pk_fma_f32 v[212:213], v[54:55], v[136:137], v[212:213]
	v_pk_fma_f32 v[210:211], v[52:53], v[134:135], v[210:211]
	v_pk_fma_f32 v[216:217], v[42:43], v[132:133], v[216:217]
	v_pk_fma_f32 v[214:215], v[40:41], v[130:131], v[214:215]
	v_lshl_add_u64 v[234:235], v[182:183], 0, s[42:43]
	global_store_dwordx4 v[234:235], v[202:205], off
	global_store_dwordx4 v[234:235], v[206:209], off offset:64
	global_store_dwordx4 v[234:235], v[210:213], off offset:512
	global_store_dwordx4 v[234:235], v[214:217], off offset:576
	v_lshl_add_u64 v[182:183], v[172:173], 0, v[166:167]
	v_lshlrev_b64 v[182:183], 2, v[182:183]
	v_lshl_add_u64 v[182:183], s[36:37], 0, v[182:183]
	global_load_dwordx4 v[202:205], v[182:183], off
	global_load_dwordx4 v[206:209], v[182:183], off offset:64
	global_load_dwordx4 v[210:213], v[182:183], off offset:512
	global_load_dwordx4 v[214:217], v[182:183], off offset:576
	s_waitcnt vmcnt(16)
	v_pk_fma_f32 v[220:221], v[50:51], v[144:145], v[220:221]
	v_pk_fma_f32 v[218:219], v[48:49], v[142:143], v[218:219]
	v_pk_fma_f32 v[224:225], v[46:47], v[140:141], v[224:225]
	v_pk_fma_f32 v[222:223], v[44:45], v[138:139], v[222:223]
	v_pk_fma_f32 v[228:229], v[38:39], v[136:137], v[228:229]
	v_pk_fma_f32 v[226:227], v[36:37], v[134:135], v[226:227]
	v_pk_fma_f32 v[232:233], v[26:27], v[132:133], v[232:233]
	v_pk_fma_f32 v[230:231], v[24:25], v[130:131], v[230:231]
	v_lshl_add_u64 v[234:235], v[176:177], 0, s[42:43]
	global_store_dwordx4 v[234:235], v[218:221], off
	global_store_dwordx4 v[234:235], v[222:225], off offset:64
	global_store_dwordx4 v[234:235], v[226:229], off offset:512
	global_store_dwordx4 v[234:235], v[230:233], off offset:576
	s_waitcnt vmcnt(12)
	v_pk_fma_f32 v[186:187], v[34:35], v[144:145], v[186:187]
	v_pk_fma_f32 v[184:185], v[32:33], v[142:143], v[184:185]
	v_pk_fma_f32 v[192:193], v[30:31], v[140:141], v[192:193]
	v_pk_fma_f32 v[190:191], v[28:29], v[138:139], v[190:191]
	v_pk_fma_f32 v[196:197], v[22:23], v[136:137], v[196:197]
	v_pk_fma_f32 v[194:195], v[20:21], v[134:135], v[194:195]
	v_pk_fma_f32 v[200:201], v[10:11], v[132:133], v[200:201]
	v_pk_fma_f32 v[198:199], v[8:9], v[130:131], v[198:199]
	v_lshl_add_u64 v[234:235], v[180:181], 0, s[42:43]
	global_store_dwordx4 v[234:235], v[184:187], off
	global_store_dwordx4 v[234:235], v[190:193], off offset:64
	global_store_dwordx4 v[234:235], v[194:197], off offset:512
	global_store_dwordx4 v[234:235], v[198:201], off offset:576
	s_waitcnt vmcnt(8)
	v_pk_fma_f32 v[204:205], v[18:19], v[144:145], v[204:205]
	v_pk_fma_f32 v[202:203], v[16:17], v[142:143], v[202:203]
	v_pk_fma_f32 v[208:209], v[14:15], v[140:141], v[208:209]
	v_pk_fma_f32 v[206:207], v[12:13], v[138:139], v[206:207]
	v_pk_fma_f32 v[212:213], v[6:7], v[136:137], v[212:213]
	v_pk_fma_f32 v[210:211], v[4:5], v[134:135], v[210:211]
	v_pk_fma_f32 v[216:217], v[2:3], v[132:133], v[216:217]
	v_pk_fma_f32 v[214:215], v[0:1], v[130:131], v[214:215]
	v_lshl_add_u64 v[234:235], v[182:183], 0, s[42:43]
	global_store_dwordx4 v[234:235], v[202:205], off
	global_store_dwordx4 v[234:235], v[206:209], off offset:64
	global_store_dwordx4 v[234:235], v[210:213], off offset:512
	global_store_dwordx4 v[234:235], v[214:217], off offset:576
	s_cbranch_vccnz .LBB0_2017
	s_andn2_b64 vcc, exec, s[16:17]
	s_cbranch_vccnz .LBB0_2016
	s_barrier
	s_branch .LBB0_2016
